# also 64B-align attention tile-loop heads
# baseline (speedup 1.0000x reference)
; template <int DQK, bool NA>
; __device__ __forceinline__ void attn_unit(const UnitP& P, char* lds) {
;     ...
;     DMA(0, 0); asm volatile("s_waitcnt vmcnt(0)" ::: "memory"); __syncthreads();
;     for (int t = 0; t < P.NT; ++t) {
;         if (t + 1 < P.NT) DMA(t + 1, (t + 1) & 1);
;         bool act = true;
;         if constexpr (NA) act = (t >= P.nlat) || ((unsigned)(P.krow0 + t - r0w) < 8u);
;         if (act) {
;             const char* Kb = K_lds + (t & 1) * SHM_K;
;             f32x16 p0, p1;
; #pragma unroll
;             for (int r = 0; r < 16; ++r) { p0[r] = 0.f; p1[r] = 0.f; }
; #pragma unroll
;             for (int d0 = 0; d0 < NQ; ++d0) { const int cb = (d0 * 16 + hi * 8) * 2;
;                 const bf16x8 b0 = *reinterpret_cast<const bf16x8*>(Kb + KSWZ(r32, cb));
;                 const bf16x8 b1 = *reinterpret_cast<const bf16x8*>(Kb + KSWZ(32 + r32, cb));
;                 p0 = __builtin_amdgcn_mfma_f32_32x32x16_bf16(b0, qr[d0], p0, 0, 0, 0);
;                 p1 = __builtin_amdgcn_mfma_f32_32x32x16_bf16(b1, qr[d0], p1, 0, 0, 0); }
;             if constexpr (NA) {
;                 if (t < P.nlat) {
;                     const int dr = P.krow0 + t - qgrow + 7; const float* rp = rpbs + dr * 31;
;                     int qcx = qc, c0x = c0, hix = hi; asm volatile("" : "+v"(qcx), "+v"(c0x), "+v"(hix));
; #pragma unroll
;                     for (int r = 0; r < 16; ++r) { const int kc0 = crow(r, hix), kc1 = 32 + kc0;
;                         const float b0 = rp[min(max(kc0 - qcx + 15, 0), 30)], b1 = rp[min(max(kc1 - qcx + 15, 0), 30)];
;                         p0[r] = ((unsigned)(kc0 - c0x) < 16u) ? p0[r] + b0 : -1e30f;
;                         p1[r] = ((unsigned)(kc1 - c0x) < 16u) ? p1[r] + b1 : -1e30f;
;                         if ((r & 3) == 3) asm volatile("" ::: "memory"); }
;                 }
;             }
;             float pmax = p0[0];
; #pragma unroll
;             for (int r = 1; r < 16; ++r) pmax = fmaxf(pmax, p0[r]);
; #pragma unroll
;             for (int r = 0; r < 16; ++r) pmax = fmaxf(pmax, p1[r]);
;             { auto rr = __builtin_amdgcn_permlane32_swap(__float_as_uint(pmax), __float_as_uint(pmax), false, false);
;               pmax = fmaxf(__uint_as_float(rr[0]), __uint_as_float(rr[1])); }
;             float mn, alpha;
;             if (__all(pmax - m_reg <= P.thr_raw)) { mn = m_reg; alpha = 1.f; }
.LBB0_499:
	v_mov_b32_e32 v139, 0
	s_mov_b32 s28, 0
	v_add_u32_e32 v0, s28, v144
	v_add_u32_e32 v154, v0, v152
	v_add_u32_e32 v155, v0, v151
	v_add_u32_e32 v156, v0, v150
	v_add_u32_e32 v157, v0, v149
	v_add_u32_e32 v194, v0, v148
	v_add_u32_e32 v195, v0, v147
	v_add_u32_e32 v244, v0, v146
	v_add_u32_e32 v245, v0, v145
	ds_read_b128 v[218:221], v154 offset:32768
	ds_read_b128 v[222:225], v155 offset:32768
	ds_read_b128 v[226:229], v156 offset:32768
	ds_read_b128 v[190:193], v157 offset:32768
	s_mov_b32 s27, 1
	s_cmp_lt_u32 s27, 32
	s_cselect_b32 s8, 0, 0xffffffe0
	s_cselect_b32 s9, s72, s19
	s_add_i32 s8, s8, s27
	s_lshl_b32 s8, s8, 6
	s_add_i32 s8, s8, s9
	s_mulk_i32 s8, 0x2e40
	s_ashr_i32 s9, s8, 31
	s_lshl_b64 s[8:9], s[8:9], 1
	s_movk_i32 s28, 0x6000
	s_add_i32 s28, s10, s28
	s_add_i32 m0, s28, 0x8000
	v_lshl_add_u64 v[172:173], v[132:133], 0, s[8:9]
	global_load_lds_dwordx4 v[172:173], off
	s_add_i32 m0, s28, 0x8400
	v_lshl_add_u64 v[172:173], v[134:135], 0, s[8:9]
	global_load_lds_dwordx4 v[172:173], off
	s_waitcnt lgkmcnt(3)
	v_mfma_f32_32x32x16_bf16 v[174:189], v[218:221], v[126:129], 0
	ds_read_b128 v[218:221], v154 offset:40960
	s_waitcnt lgkmcnt(3)
	v_mfma_f32_32x32x16_bf16 v[174:189], v[222:225], v[122:125], v[174:189]
	ds_read_b128 v[222:225], v155 offset:40960
	s_waitcnt lgkmcnt(3)
	v_mfma_f32_32x32x16_bf16 v[174:189], v[226:229], v[118:121], v[174:189]
	ds_read_b128 v[226:229], v194 offset:32768
	s_waitcnt lgkmcnt(3)
	v_mfma_f32_32x32x16_bf16 v[174:189], v[190:193], v[114:117], v[174:189]
	ds_read_b128 v[190:193], v195 offset:32768
	s_waitcnt lgkmcnt(3)
	v_mfma_f32_32x32x16_bf16 v[202:217], v[218:221], v[126:129], 0
	ds_read_b128 v[218:221], v244 offset:32768
	s_waitcnt lgkmcnt(3)
	v_mfma_f32_32x32x16_bf16 v[202:217], v[222:225], v[122:125], v[202:217]
	ds_read_b128 v[222:225], v245 offset:32768
	s_waitcnt lgkmcnt(3)
	v_mfma_f32_32x32x16_bf16 v[174:189], v[226:229], v[110:113], v[174:189]
	ds_read_b128 v[226:229], v156 offset:40960
	s_waitcnt lgkmcnt(3)
	v_mfma_f32_32x32x16_bf16 v[174:189], v[190:193], v[106:109], v[174:189]
	ds_read_b128 v[190:193], v157 offset:40960
	s_waitcnt lgkmcnt(3)
	v_mfma_f32_32x32x16_bf16 v[174:189], v[218:221], v[102:105], v[174:189]
	ds_read_b128 v[218:221], v194 offset:40960
	s_waitcnt lgkmcnt(3)
	v_mfma_f32_32x32x16_bf16 v[174:189], v[222:225], v[98:101], v[174:189]
	ds_read_b128 v[222:225], v195 offset:40960
	s_waitcnt lgkmcnt(3)
	v_mfma_f32_32x32x16_bf16 v[202:217], v[226:229], v[118:121], v[202:217]
	ds_read_b128 v[226:229], v244 offset:40960
	s_waitcnt lgkmcnt(3)
	v_mfma_f32_32x32x16_bf16 v[202:217], v[190:193], v[114:117], v[202:217]
	ds_read_b128 v[190:193], v245 offset:40960
	s_waitcnt lgkmcnt(3)
	v_mfma_f32_32x32x16_bf16 v[202:217], v[218:221], v[110:113], v[202:217]
	s_waitcnt lgkmcnt(2)
	v_mfma_f32_32x32x16_bf16 v[202:217], v[222:225], v[106:109], v[202:217]
	s_waitcnt lgkmcnt(1)
	v_mfma_f32_32x32x16_bf16 v[202:217], v[226:229], v[102:105], v[202:217]
	s_waitcnt lgkmcnt(0)
	v_mfma_f32_32x32x16_bf16 v[202:217], v[190:193], v[98:101], v[202:217]
	s_nop 11
	v_max_f32_e32 v138, v174, v174
	v_max_f32_e32 v0, v175, v175
	v_max_f32_e32 v0, v138, v0
	v_max3_f32 v0, v0, v176, v177
	v_max3_f32 v0, v0, v178, v179
	v_max3_f32 v0, v0, v180, v181
	v_max3_f32 v0, v0, v182, v183
	v_max3_f32 v0, v0, v184, v185
	v_max3_f32 v0, v0, v186, v187
	v_max3_f32 v0, v0, v188, v189
	v_max3_f32 v0, v0, v202, v203
	v_max3_f32 v0, v0, v204, v205
	v_max3_f32 v0, v0, v206, v207
	v_max3_f32 v0, v0, v208, v209
	v_max3_f32 v0, v0, v210, v211
	v_max3_f32 v0, v0, v212, v213
	v_max3_f32 v0, v0, v214, v215
	v_max3_f32 v0, v0, v216, v217
	v_mov_b32_e32 v138, v0
	s_nop 1
	v_permlane32_swap_b32_e32 v0, v138
	v_max_f32_e32 v138, v138, v138
	v_max_f32_e32 v0, v0, v0
	v_max_f32_e32 v0, v0, v138
	v_sub_f32_e32 v138, v0, v143
	v_cmp_ge_f32_e32 vcc, s79, v138
	s_cmp_eq_u64 vcc, exec
	v_max_f32_e32 v138, v143, v143
	v_max_f32_e32 v0, v138, v0
	s_cselect_b64 vcc, -1, 0
	v_sub_f32_e32 v138, v143, v0
	v_cndmask_b32_e32 v143, v0, v143, vcc
	v_mul_f32_e32 v153, 0xbe0293ee, v143
	v_mul_f32_e32 v0, 0x3e0293ee, v138
	v_exp_f32_e32 v0, v0
	s_nop 0
	v_cndmask_b32_e64 v247, v0, 1.0, vcc
	v_mov_b64_e32 v[66:67], v[174:175]
	v_mov_b64_e32 v[68:69], v[176:177]
	v_mov_b64_e32 v[70:71], v[178:179]
	v_mov_b64_e32 v[72:73], v[180:181]
	v_mov_b64_e32 v[74:75], v[182:183]
	v_mov_b64_e32 v[76:77], v[184:185]
	v_mov_b64_e32 v[78:79], v[186:187]
	v_mov_b64_e32 v[80:81], v[188:189]
	v_mov_b64_e32 v[82:83], v[202:203]
	v_mov_b64_e32 v[84:85], v[204:205]
	v_mov_b64_e32 v[86:87], v[206:207]
	v_mov_b64_e32 v[88:89], v[208:209]
	v_mov_b64_e32 v[90:91], v[210:211]
	v_mov_b64_e32 v[92:93], v[212:213]
	v_mov_b64_e32 v[94:95], v[214:215]
	v_mov_b64_e32 v[96:97], v[216:217]
	s_waitcnt vmcnt(0)
	s_barrier
	.p2align	6

; template <int DQK, bool NA>
; __device__ __forceinline__ void attn_unit(const UnitP& P, char* lds) {
;     ...
;     bf16x8 qr[NQ];
;     { const bf16_t* Qw = P.Q + (size_t)(wid * 32 + r32) * P.ldq + hi * 8;
; #pragma unroll
;       for (int d0 = 0; d0 < NQ; ++d0) qr[d0] = *reinterpret_cast<const bf16x8*>(Qw + d0 * 16); }
;     if constexpr (DQK == 192) {
;         if (P.rope_q) {
;             const int s = P.qpos0 + wid * 32 + r32; const float prow = (float)(s >> 6), pcol = (float)(s & 63);
; #pragma unroll
;             for (int e = 0; e < 8; ++e) {
;                 const float fr_ = __builtin_amdgcn_exp2f(-(float)(hi * 8 + e) * (13.287712379549449f / 16.f));
;                 const float ar = prow * fr_, ac = pcol * fr_;
;                 const float cr = __cosf(ar), sr = __sinf(ar), cc = __cosf(ac), sc = __sinf(ac);
;                 const float x1 = bf2f((unsigned short)qr[8][e]), x2 = bf2f((unsigned short)qr[9][e]), y1 = bf2f((unsigned short)qr[10][e]), y2 = bf2f((unsigned short)qr[11][e]);
;                 const unsigned w0 = cvtpk(x1 * cr - x2 * sr, x2 * cr + x1 * sr), w1 = cvtpk(y1 * cc - y2 * sc, y2 * cc + y1 * sc);
;                 qr[8][e] = (short)(w0 & 0xffffu); qr[9][e] = (short)(w0 >> 16); qr[10][e] = (short)(w1 & 0xffffu); qr[11][e] = (short)(w1 >> 16);
;             }
;         }
;     }
;     const int vb0 = (int)(uintptr_t)V_lds + v_rd_base(lane);
;     ...
;     LAS char* ldsl = (LAS char*)lds;
;     constexpr int NKI = DQK / 64;
;     int voffe[2]; const bf16_t* kbase[NKI]; int kld[NKI];
; #pragma unroll
;     for (int j = 0; j < 2; ++j) { const int X = (wid * 2 + j) * 1024 + lane * 16, st = X >> 9, kk = ((st >> 2) << 3) | ((X >> 6) & 7), c = ((st & 3) << 5) | ((X >> 1) & 31);
;         const int k = (kk & ~0xC) | ((kk & 4) << 1) | ((kk & 8) >> 1); voffe[j] = k * P.ldv + c; }
; #pragma unroll
;     for (int j = 0; j < NKI; ++j) { const int X = (wid * NKI + j) * 1024 + lane * 16, row = X / KROWB, cb = X - row * KROWB, colB = cb ^ ((row & 7) << 4);
;         if (DQK == 192 && colB >= 256) { kbase[j] = P.K2 + (size_t)row * P.ldk2 + ((colB - 256) >> 1); kld[j] = P.ldk2; }
;         else { kbase[j] = P.K1 + (size_t)row * P.ldk1 + (colB >> 1); kld[j] = P.ldk1; } }
;     ...
;     const int qgrow = P.qgrow0 + (wid >> 1), qc = (wid & 1) * 32 + r32;
;     const int r0w = min(max(qgrow - 4, 0), 24), c0 = min(max(qc - 8, 0), 48);
.LBB0_523:
	s_or_b64 exec, exec, s[4:5]
	s_and_b32 s4, s26, 0x3fffffc0
	s_lshl_b32 s4, s4, 2
	s_add_i32 s24, s4, 0
	s_lshl_b32 s4, s25, 11
	s_ashr_i32 s5, s4, 8
	v_lshrrev_b32_e32 v23, 1, v18
	v_bfe_u32 v0, v18, 2, 2
	s_and_b32 s25, s5, 0xfffff0
	v_and_b32_e32 v23, 8, v23
	s_lshr_b32 s5, s5, 1
	v_or3_b32 v0, v23, v0, s25
	v_lshlrev_b32_e32 v17, 3, v19
	v_and_or_b32 v0, s5, 4, v0
	v_and_b32_e32 v28, 24, v17
	v_and_b32_e32 v22, 32, v18
	v_mul_i32_i24_e32 v0, 0x840, v0
	s_add_i32 s24, s24, 0x14000
	v_or3_b32 v22, v0, v22, v28
	s_add_i32 s25, s4, 0
	s_mul_i32 s4, s72, 0x1080
	s_add_u32 s4, s8, s4
	v_ashrrev_i32_e32 v23, 31, v22
	s_addc_u32 s5, s9, 0
	v_lshlrev_b64 v[22:23], 1, v[22:23]
	v_lshl_add_u64 v[24:25], s[4:5], 0, v[22:23]
	v_lshl_add_u64 v[26:27], v[24:25], 0, s[54:55]
	s_mov_b32 m0, s25
	v_mul_u32_u24_e32 v0, s72, v150
	global_load_lds_dwordx4 v[26:27], off
	v_lshl_add_u64 v[24:25], v[24:25], 0, s[22:23]
	s_add_i32 m0, s25, 0x400
	v_lshlrev_b32_e32 v0, 1, v0
	global_load_lds_dwordx4 v[24:25], off
	v_lshl_add_u64 v[24:25], v[148:149], 0, v[0:1]
	s_add_i32 s26, s27, 0
	v_mul_u32_u24_e32 v0, s72, v154
	s_add_i32 m0, s26, 0x8000
	v_lshlrev_b32_e32 v0, 1, v0
	global_load_lds_dwordx4 v[24:25], off
	v_lshl_add_u64 v[24:25], v[152:153], 0, v[0:1]
	v_mul_u32_u24_e32 v0, s72, v158
	s_add_i32 m0, s26, 0x8400
	v_lshlrev_b32_e32 v0, 1, v0
	global_load_lds_dwordx4 v[24:25], off
	v_lshl_add_u64 v[24:25], v[156:157], 0, v[0:1]
	s_add_i32 m0, s26, 0x8800
	v_lshlrev_b32_e32 v18, 4, v18
	global_load_lds_dwordx4 v[24:25], off
	s_movk_i32 s28, 0x180
	v_and_b32_e32 v24, 0x70, v18
	v_mad_u32_u24 v176, v165, s28, 0
	s_movk_i32 s28, 0x60
	v_bitop3_b32 v173, v146, v24, s28 bitop3:0x36
	s_movk_i32 s28, 0x80
	v_bitop3_b32 v172, v146, v24, s28 bitop3:0x36
	s_movk_i32 s28, 0xa0
	v_bitop3_b32 v171, v146, v24, s28 bitop3:0x36
	s_movk_i32 s28, 0xc0
	v_bitop3_b32 v170, v146, v24, s28 bitop3:0x36
	s_movk_i32 s28, 0xe0
	v_bitop3_b32 v169, v146, v24, s28 bitop3:0x36
	s_movk_i32 s28, 0x120
	v_lshlrev_b32_e32 v0, 1, v19
	v_and_b32_e32 v9, 0xc0, v9
	v_and_b32_e32 v17, 0x100, v17
	v_bitop3_b32 v167, v146, v24, s28 bitop3:0x36
	s_mov_b32 s28, 0x7060302
	s_movk_i32 s29, 0x140
	s_cmp_lg_u32 0, -1
	v_and_b32_e32 v0, 32, v0
	v_perm_b32 v141, v13, v8, s28
	v_perm_b32 v140, v12, v7, s28
	v_perm_b32 v139, v11, v6, s28
	v_perm_b32 v138, v10, v21, s28
	v_bitop3_b32 v159, v146, v24, s29 bitop3:0x36
	v_perm_b32 v132, v4, v15, s35
	v_perm_b32 v131, v3, v14, s35
	v_perm_b32 v130, v2, v20, s35
	s_movk_i32 s29, 0x160
	v_perm_b32 v137, v5, v16, s28
	v_perm_b32 v136, v4, v15, s28
	v_perm_b32 v135, v3, v14, s28
	v_perm_b32 v134, v2, v20, s28
	v_or3_b32 v2, v9, v17, v28
	s_cselect_b32 s28, 0, 0
	v_mov_b32_e32 v14, v1
	v_mov_b32_e32 v15, v1
	s_waitcnt vmcnt(0)
	v_cmp_gt_u32_e64 s[4:5], 32, v19
	v_bitop3_b32 v177, v146, v18, s94 bitop3:0x78
	v_bitop3_b32 v175, v146, v24, 32 bitop3:0x36
	v_bitop3_b32 v174, v146, v24, 64 bitop3:0x36
	v_bitop3_b32 v168, v146, v24, s93 bitop3:0x36
	v_perm_b32 v145, v13, v8, s35
	v_perm_b32 v144, v12, v7, s35
	v_perm_b32 v143, v11, v6, s35
	v_perm_b32 v142, v10, v21, s35
	v_perm_b32 v133, v5, v16, s35
	v_bitop3_b32 v166, v146, v24, s29 bitop3:0x36
	v_add3_u32 v151, v0, s28, v2
	v_lshl_add_u64 v[160:161], s[8:9], 0, v[22:23]
	v_mov_b32_e32 v0, v1
	v_mov_b32_e32 v2, v1
	v_mov_b32_e32 v3, v1
	v_mov_b32_e32 v4, v1
	v_mov_b32_e32 v5, v1
	v_mov_b32_e32 v6, v1
	v_mov_b32_e32 v7, v1
	v_mov_b32_e32 v8, v1
	v_mov_b32_e32 v9, v1
	v_mov_b32_e32 v10, v1
	v_mov_b32_e32 v11, v1
	v_mov_b32_e32 v12, v1
	v_mov_b32_e32 v13, v1
	v_mov_b64_e32 v[64:65], v[14:15]
	v_mov_b64_e32 v[48:49], v[14:15]
	v_mov_b64_e32 v[32:33], v[14:15]
	v_mov_b64_e32 v[62:63], v[12:13]
	v_mov_b64_e32 v[60:61], v[10:11]
	v_mov_b64_e32 v[58:59], v[8:9]
	v_mov_b64_e32 v[56:57], v[6:7]
	v_mov_b64_e32 v[54:55], v[4:5]
	v_mov_b64_e32 v[52:53], v[2:3]
	v_mov_b64_e32 v[50:51], v[0:1]
	v_mov_b64_e32 v[46:47], v[12:13]
	v_mov_b64_e32 v[44:45], v[10:11]
	v_mov_b64_e32 v[42:43], v[8:9]
	v_mov_b64_e32 v[40:41], v[6:7]
	v_mov_b64_e32 v[38:39], v[4:5]
	v_mov_b64_e32 v[36:37], v[2:3]
	v_mov_b64_e32 v[34:35], v[0:1]
	v_mov_b64_e32 v[30:31], v[12:13]
	v_mov_b64_e32 v[28:29], v[10:11]
	v_mov_b64_e32 v[26:27], v[8:9]
	v_mov_b64_e32 v[24:25], v[6:7]
	v_mov_b64_e32 v[22:23], v[4:5]
	v_mov_b64_e32 v[20:21], v[2:3]
	v_mov_b64_e32 v[18:19], v[0:1]
	v_mov_b64_e32 v[16:17], v[14:15]
	s_mov_b32 s27, 1
	v_lshl_add_u32 v147, v165, 2, s24
	v_mov_b32_e32 v178, 0
	v_mov_b32_e32 v155, 0xf149f2ca
	s_movk_i32 s56, 0x4000
	v_mov_b64_e32 v[14:15], v[12:13]
	v_mov_b64_e32 v[12:13], v[10:11]
	v_mov_b64_e32 v[10:11], v[8:9]
	v_mov_b64_e32 v[8:9], v[6:7]
	v_mov_b64_e32 v[6:7], v[4:5]
	v_mov_b64_e32 v[4:5], v[2:3]
	v_mov_b64_e32 v[2:3], v[0:1]
	s_waitcnt vmcnt(0) lgkmcnt(0)
	s_barrier
	.p2align	6

; template <int DQK, bool NA>
; __device__ __forceinline__ void attn_unit(const UnitP& P, char* lds) {
;     ...
;     const int qgrow = P.qgrow0 + (wid >> 1), qc = (wid & 1) * 32 + r32;
;     const int r0w = min(max(qgrow - 4, 0), 24), c0 = min(max(qc - 8, 0), 48);
;     DMA(0, 0); asm volatile("s_waitcnt vmcnt(0)" ::: "memory"); __syncthreads();
;     for (int t = 0; t < P.NT; ++t) {
;         if (t + 1 < P.NT) DMA(t + 1, (t + 1) & 1);
;         bool act = true;
;         if constexpr (NA) act = (t >= P.nlat) || ((unsigned)(P.krow0 + t - r0w) < 8u);
.LBB0_547:
	s_cmp_lt_i32 s26, s10
	s_cselect_b32 s6, 0, s11
	s_cselect_b32 s7, s12, s19
	s_lshl_b32 s6, s6, 6
	s_sub_i32 s6, s7, s6
	s_add_i32 s27, s14, s6
	s_and_b32 s6, s21, 0x4000
	s_add_i32 s28, s13, s6
	v_mad_i64_i32 v[68:69], s[6:7], s27, v241, v[136:137]
	s_mov_b32 m0, s28
	s_nop 0
	global_load_lds_dwordx4 v[68:69], off
	s_add_i32 m0, s28, 0x400
	s_bitcmp1_b32 s25, 0
	s_cselect_b32 s6, 0x6000, 0
	v_lshl_add_u64 v[68:69], v[68:69], 0, s[40:41]
	s_add_i32 s28, s13, s6
	global_load_lds_dwordx4 v[68:69], off
	s_add_i32 m0, s28, 0x8000
	v_mad_i64_i32 v[68:69], s[6:7], s27, v241, v[132:133]
	global_load_lds_dwordx4 v[68:69], off
	v_mad_i64_i32 v[68:69], s[6:7], s27, v241, v[134:135]
	s_add_i32 m0, s28, 0x8400
	s_nop 0
	global_load_lds_dwordx4 v[68:69], off
	.p2align	6

; template <int DQK, bool NA>
; __device__ __forceinline__ void attn_unit(const UnitP& P, char* lds) {
;     ...
;     bf16x8 qr[NQ];
;     { const bf16_t* Qw = P.Q + (size_t)(wid * 32 + r32) * P.ldq + hi * 8;
; #pragma unroll
;       for (int d0 = 0; d0 < NQ; ++d0) qr[d0] = *reinterpret_cast<const bf16x8*>(Qw + d0 * 16); }
;     if constexpr (DQK == 192) {
;         if (P.rope_q) {
;             const int s = P.qpos0 + wid * 32 + r32; const float prow = (float)(s >> 6), pcol = (float)(s & 63);
; #pragma unroll
;             for (int e = 0; e < 8; ++e) {
;                 const float fr_ = __builtin_amdgcn_exp2f(-(float)(hi * 8 + e) * (13.287712379549449f / 16.f));
;                 const float ar = prow * fr_, ac = pcol * fr_;
;                 const float cr = __cosf(ar), sr = __sinf(ar), cc = __cosf(ac), sc = __sinf(ac);
;                 const float x1 = bf2f((unsigned short)qr[8][e]), x2 = bf2f((unsigned short)qr[9][e]), y1 = bf2f((unsigned short)qr[10][e]), y2 = bf2f((unsigned short)qr[11][e]);
;                 const unsigned w0 = cvtpk(x1 * cr - x2 * sr, x2 * cr + x1 * sr), w1 = cvtpk(y1 * cc - y2 * sc, y2 * cc + y1 * sc);
;                 qr[8][e] = (short)(w0 & 0xffffu); qr[9][e] = (short)(w0 >> 16); qr[10][e] = (short)(w1 & 0xffffu); qr[11][e] = (short)(w1 >> 16);
;             }
;         }
;     }
;     const int vb0 = (int)(uintptr_t)V_lds + v_rd_base(lane);
;     ...
;     LAS char* ldsl = (LAS char*)lds;
;     constexpr int NKI = DQK / 64;
;     int voffe[2]; const bf16_t* kbase[NKI]; int kld[NKI];
; #pragma unroll
;     for (int j = 0; j < 2; ++j) { const int X = (wid * 2 + j) * 1024 + lane * 16, st = X >> 9, kk = ((st >> 2) << 3) | ((X >> 6) & 7), c = ((st & 3) << 5) | ((X >> 1) & 31);
;         const int k = (kk & ~0xC) | ((kk & 4) << 1) | ((kk & 8) >> 1); voffe[j] = k * P.ldv + c; }
; #pragma unroll
;     for (int j = 0; j < NKI; ++j) { const int X = (wid * NKI + j) * 1024 + lane * 16, row = X / KROWB, cb = X - row * KROWB, colB = cb ^ ((row & 7) << 4);
;         if (DQK == 192 && colB >= 256) { kbase[j] = P.K2 + (size_t)row * P.ldk2 + ((colB - 256) >> 1); kld[j] = P.ldk2; }
;         else { kbase[j] = P.K1 + (size_t)row * P.ldk1 + (colB >> 1); kld[j] = P.ldk1; } }
;     ...
;     const int qgrow = P.qgrow0 + (wid >> 1), qc = (wid & 1) * 32 + r32;
;     const int r0w = min(max(qgrow - 4, 0), 24), c0 = min(max(qc - 8, 0), 48);
.LBB0_580:
	s_or_b64 exec, exec, s[8:9]
	s_and_b32 s8, s11, 0x3fffffc0
	s_lshl_b32 s8, s8, 2
	s_add_i32 s11, s8, 0
	s_lshl_b32 s8, s19, 11
	s_ashr_i32 s9, s8, 8
	v_lshrrev_b32_e32 v17, 1, v14
	v_bfe_u32 v9, v14, 2, 2
	s_and_b32 s19, s9, 0xfffff0
	v_and_b32_e32 v17, 8, v17
	s_lshr_b32 s9, s9, 1
	v_or3_b32 v9, v17, v9, s19
	v_lshlrev_b32_e32 v0, 3, v15
	v_and_or_b32 v9, s9, 4, v9
	v_and_b32_e32 v5, 24, v0
	v_and_b32_e32 v13, 32, v14
	v_mul_i32_i24_e32 v9, 0x840, v9
	s_add_i32 s11, s11, 0x14000
	v_or3_b32 v18, v9, v13, v5
	s_lshl_b32 s24, s18, 9
	s_add_i32 s19, s8, 0
	s_mul_i32 s26, s7, 0x1080
	s_mul_hi_u32 s25, s7, 0x1080
	s_add_u32 s4, s4, s26
	v_ashrrev_i32_e32 v19, 31, v18
	s_addc_u32 s5, s5, s25
	v_lshlrev_b64 v[18:19], 1, v[18:19]
	v_lshl_add_u64 v[20:21], s[4:5], 0, v[18:19]
	v_lshl_add_u64 v[22:23], v[20:21], 0, s[54:55]
	s_mov_b32 m0, s19
	v_lshl_add_u64 v[20:21], v[20:21], 0, s[22:23]
	global_load_lds_dwordx4 v[22:23], off
	s_add_i32 m0, s19, 0x400
	s_add_i32 s20, s20, 0
	global_load_lds_dwordx4 v[20:21], off
	v_mad_u64_u32 v[20:21], s[4:5], v4, s7, 0
	v_lshl_add_u64 v[20:21], v[20:21], 1, v[2:3]
	s_add_i32 m0, s20, 0x8000
	v_lshlrev_b32_e32 v14, 4, v14
	global_load_lds_dwordx4 v[20:21], off
	v_mad_u64_u32 v[20:21], s[4:5], v8, s7, 0
	v_lshl_add_u64 v[20:21], v[20:21], 1, v[6:7]
	s_add_i32 m0, s20, 0x8400
	s_movk_i32 s8, 0x180
	global_load_lds_dwordx4 v[20:21], off
	v_mad_u64_u32 v[20:21], s[4:5], v12, s7, 0
	v_lshl_add_u64 v[20:21], v[20:21], 1, v[10:11]
	s_add_i32 m0, s20, 0x8800
	v_and_b32_e32 v13, 0xc0, v16
	global_load_lds_dwordx4 v[20:21], off
	v_and_b32_e32 v16, 0x70, v14
	v_mad_u32_u24 v179, v165, s8, 0
	s_movk_i32 s8, 0x60
	v_bitop3_b32 v176, v146, v16, s8 bitop3:0x36
	s_movk_i32 s8, 0x80
	v_bitop3_b32 v175, v146, v16, s8 bitop3:0x36
	s_movk_i32 s8, 0xa0
	v_bitop3_b32 v174, v146, v16, s8 bitop3:0x36
	s_movk_i32 s8, 0xc0
	v_bitop3_b32 v173, v146, v16, s8 bitop3:0x36
	s_movk_i32 s8, 0xe0
	v_bitop3_b32 v172, v146, v16, s8 bitop3:0x36
	s_movk_i32 s8, 0x120
	v_bitop3_b32 v170, v146, v16, s8 bitop3:0x36
	s_movk_i32 s8, 0x140
	v_lshlrev_b32_e32 v9, 1, v15
	v_and_b32_e32 v0, 0x100, v0
	v_bitop3_b32 v169, v146, v16, s8 bitop3:0x36
	s_movk_i32 s8, 0x160
	s_cmp_lg_u32 0, -1
	v_and_b32_e32 v9, 32, v9
	v_bitop3_b32 v168, v146, v16, s8 bitop3:0x36
	v_or3_b32 v0, v13, v0, v5
	s_cselect_b32 s8, 0, 0
	v_add3_u32 v166, v9, s8, v0
	v_lshlrev_b32_e32 v0, 1, v12
	s_add_u32 s27, s7, 64
	s_addc_u32 s28, 0, 0
	v_mad_u64_u32 v[148:149], s[8:9], v0, s27, v[10:11]
	v_mad_u32_u24 v149, v0, s28, v149
	v_lshlrev_b32_e32 v0, 1, v8
	v_mad_u64_u32 v[152:153], s[8:9], v0, s27, v[6:7]
	v_mad_u32_u24 v153, v0, s28, v153
	v_lshlrev_b32_e32 v0, 1, v4
	v_mad_u64_u32 v[156:157], s[8:9], v0, s27, v[2:3]
	s_add_u32 s8, s26, s24
	s_addc_u32 s9, s25, 0
	v_readlane_b32 s24, v250, 58
	s_add_u32 s8, s24, s8
	v_readlane_b32 s24, v250, 59
	v_cmp_gt_u32_e64 s[4:5], 32, v15
	v_bitop3_b32 v180, v146, v14, s94 bitop3:0x78
	s_addc_u32 s9, s24, s9
	v_mov_b32_e32 v14, v1
	v_mov_b32_e32 v15, v1
	s_waitcnt vmcnt(0)
	v_lshlrev_b32_e32 v150, 7, v12
	v_lshlrev_b32_e32 v154, 7, v8
	v_mad_u32_u24 v157, v0, s28, v157
	v_lshlrev_b32_e32 v158, 7, v4
	v_lshl_add_u64 v[160:161], s[8:9], 0, v[18:19]
	v_mov_b32_e32 v0, v1
	v_mov_b32_e32 v2, v1
	v_mov_b32_e32 v3, v1
	v_mov_b32_e32 v4, v1
	v_mov_b32_e32 v5, v1
	v_mov_b32_e32 v6, v1
	v_mov_b32_e32 v7, v1
	v_mov_b32_e32 v8, v1
	v_mov_b32_e32 v9, v1
	v_mov_b32_e32 v10, v1
	v_mov_b32_e32 v11, v1
	v_mov_b32_e32 v12, v1
	v_mov_b32_e32 v13, v1
	v_mov_b64_e32 v[64:65], v[14:15]
	v_mov_b64_e32 v[48:49], v[14:15]
	v_mov_b64_e32 v[32:33], v[14:15]
	v_bitop3_b32 v178, v146, v16, 32 bitop3:0x36
	v_bitop3_b32 v177, v146, v16, 64 bitop3:0x36
	v_bitop3_b32 v171, v146, v16, s93 bitop3:0x36
	v_mov_b64_e32 v[62:63], v[12:13]
	v_mov_b64_e32 v[60:61], v[10:11]
	v_mov_b64_e32 v[58:59], v[8:9]
	v_mov_b64_e32 v[56:57], v[6:7]
	v_mov_b64_e32 v[54:55], v[4:5]
	v_mov_b64_e32 v[52:53], v[2:3]
	v_mov_b64_e32 v[50:51], v[0:1]
	v_mov_b64_e32 v[46:47], v[12:13]
	v_mov_b64_e32 v[44:45], v[10:11]
	v_mov_b64_e32 v[42:43], v[8:9]
	v_mov_b64_e32 v[40:41], v[6:7]
	v_mov_b64_e32 v[38:39], v[4:5]
	v_mov_b64_e32 v[36:37], v[2:3]
	v_mov_b64_e32 v[34:35], v[0:1]
	v_mov_b64_e32 v[30:31], v[12:13]
	v_mov_b64_e32 v[28:29], v[10:11]
	v_mov_b64_e32 v[26:27], v[8:9]
	v_mov_b64_e32 v[24:25], v[6:7]
	v_mov_b64_e32 v[22:23], v[4:5]
	v_mov_b64_e32 v[20:21], v[2:3]
	v_mov_b64_e32 v[18:19], v[0:1]
	v_mov_b64_e32 v[16:17], v[14:15]
	v_lshl_add_u32 v147, v165, 2, s11
	s_mov_b32 s21, 0
	v_mov_b32_e32 v151, v1
	v_mov_b32_e32 v155, v1
	v_mov_b32_e32 v159, v1
	v_mov_b32_e32 v181, 0
	v_mov_b32_e32 v167, 0xf149f2ca
	s_movk_i32 s24, 0x4000
	v_mov_b64_e32 v[14:15], v[12:13]
	v_mov_b64_e32 v[12:13], v[10:11]
	v_mov_b64_e32 v[10:11], v[8:9]
	v_mov_b64_e32 v[8:9], v[6:7]
	v_mov_b64_e32 v[6:7], v[4:5]
	v_mov_b64_e32 v[4:5], v[2:3]
	v_mov_b64_e32 v[2:3], v[0:1]
	s_waitcnt vmcnt(0) lgkmcnt(0)
	s_barrier
	.p2align	6

; template <int DQK, bool NA>
; __device__ __forceinline__ void attn_unit(const UnitP& P, char* lds) {
;     ...
;     bf16x8 qr[NQ];
;     { const bf16_t* Qw = P.Q + (size_t)(wid * 32 + r32) * P.ldq + hi * 8;
; #pragma unroll
;       for (int d0 = 0; d0 < NQ; ++d0) qr[d0] = *reinterpret_cast<const bf16x8*>(Qw + d0 * 16); }
;     if constexpr (DQK == 192) {
;         if (P.rope_q) {
;             const int s = P.qpos0 + wid * 32 + r32; const float prow = (float)(s >> 6), pcol = (float)(s & 63);
; #pragma unroll
;             for (int e = 0; e < 8; ++e) {
;                 const float fr_ = __builtin_amdgcn_exp2f(-(float)(hi * 8 + e) * (13.287712379549449f / 16.f));
;                 const float ar = prow * fr_, ac = pcol * fr_;
;                 const float cr = __cosf(ar), sr = __sinf(ar), cc = __cosf(ac), sc = __sinf(ac);
;                 const float x1 = bf2f((unsigned short)qr[8][e]), x2 = bf2f((unsigned short)qr[9][e]), y1 = bf2f((unsigned short)qr[10][e]), y2 = bf2f((unsigned short)qr[11][e]);
;                 const unsigned w0 = cvtpk(x1 * cr - x2 * sr, x2 * cr + x1 * sr), w1 = cvtpk(y1 * cc - y2 * sc, y2 * cc + y1 * sc);
;                 qr[8][e] = (short)(w0 & 0xffffu); qr[9][e] = (short)(w0 >> 16); qr[10][e] = (short)(w1 & 0xffffu); qr[11][e] = (short)(w1 >> 16);
;             }
;         }
;     }
;     const int vb0 = (int)(uintptr_t)V_lds + v_rd_base(lane);
;     ...
;     LAS char* ldsl = (LAS char*)lds;
;     constexpr int NKI = DQK / 64;
;     int voffe[2]; const bf16_t* kbase[NKI]; int kld[NKI];
; #pragma unroll
;     for (int j = 0; j < 2; ++j) { const int X = (wid * 2 + j) * 1024 + lane * 16, st = X >> 9, kk = ((st >> 2) << 3) | ((X >> 6) & 7), c = ((st & 3) << 5) | ((X >> 1) & 31);
;         const int k = (kk & ~0xC) | ((kk & 4) << 1) | ((kk & 8) >> 1); voffe[j] = k * P.ldv + c; }
; #pragma unroll
;     for (int j = 0; j < NKI; ++j) { const int X = (wid * NKI + j) * 1024 + lane * 16, row = X / KROWB, cb = X - row * KROWB, colB = cb ^ ((row & 7) << 4);
;         if (DQK == 192 && colB >= 256) { kbase[j] = P.K2 + (size_t)row * P.ldk2 + ((colB - 256) >> 1); kld[j] = P.ldk2; }
;         else { kbase[j] = P.K1 + (size_t)row * P.ldk1 + (colB >> 1); kld[j] = P.ldk1; } }
;     ...
;     const int qgrow = P.qgrow0 + (wid >> 1), qc = (wid & 1) * 32 + r32;
;     const int r0w = min(max(qgrow - 4, 0), 24), c0 = min(max(qc - 8, 0), 48);
.LBB0_594:
	s_and_b64 vcc, exec, s[4:5]
	s_cbranch_vccz .LBB0_609
	s_lshl_b32 s4, s12, 1
	s_and_b32 s44, s4, 0x100
	s_mul_i32 s4, s16, 0x5c80
	s_mul_hi_u32 s5, s15, 0x5c80
	s_add_i32 s5, s5, s4
	s_mul_i32 s4, s15, 0x5c80
	s_add_u32 s4, s84, s4
	s_addc_u32 s5, s85, s5
	s_lshl_b32 s19, s17, 7
	s_lshl_b32 s8, s17, 8
	s_add_u32 s4, s4, s8
	s_addc_u32 s5, s5, 0
	s_add_u32 s4, s4, 0x1800
	s_addc_u32 s5, s5, 0
	s_lshl_b32 s8, s14, 6
	s_and_b32 s10, s8, 0x100
	v_readlane_b32 s8, v252, 20
	s_add_u32 s8, s8, s10
	v_readlane_b32 s9, v252, 21
	s_addc_u32 s9, s9, 0
	v_readlane_b32 s11, v252, 22
	v_mov_b32_e32 v0, v196
	s_add_u32 s10, s11, s10
	v_readlane_b32 s11, v252, 23
	s_addc_u32 s11, s11, 0
	v_readfirstlane_b32 s20, v0
	s_ashr_i32 s24, s20, 6
	s_and_b32 s20, s20, 0x3fffffc0
	s_lshl_b32 s20, s20, 2
	v_and_b32_e32 v141, 31, v0
	s_add_i32 s21, s20, 0
	s_lshl_b32 s20, s24, 5
	v_or_b32_e32 v4, s20, v141
	v_mov_b64_e32 v[2:3], s[4:5]
	v_bfe_u32 v140, v0, 5, 1
	v_mad_i64_i32 v[2:3], s[4:5], v4, s71, v[2:3]
	v_lshlrev_b32_e32 v130, 4, v140
	v_mov_b32_e32 v131, v1
	s_lshl_b32 s4, s24, 11
	v_lshl_add_u64 v[2:3], v[2:3], 0, v[130:131]
	s_ashr_i32 s5, s4, 8
	v_lshrrev_b32_e32 v4, 1, v0
	global_load_dwordx4 v[126:129], v[2:3], off
	global_load_dwordx4 v[122:125], v[2:3], off offset:32
	global_load_dwordx4 v[118:121], v[2:3], off offset:64
	global_load_dwordx4 v[114:117], v[2:3], off offset:96
	global_load_dwordx4 v[110:113], v[2:3], off offset:128
	global_load_dwordx4 v[106:109], v[2:3], off offset:160
	global_load_dwordx4 v[102:105], v[2:3], off offset:192
	global_load_dwordx4 v[98:101], v[2:3], off offset:224
	v_bfe_u32 v2, v0, 2, 2
	s_and_b32 s25, s5, 0xfffff0
	v_and_b32_e32 v4, 8, v4
	v_and_b32_e32 v18, 63, v0
	s_lshr_b32 s5, s5, 1
	v_or3_b32 v2, v4, v2, s25
	v_lshlrev_b32_e32 v19, 3, v18
	v_and_or_b32 v2, s5, 4, v2
	v_and_b32_e32 v20, 24, v19
	v_lshlrev_b32_e32 v21, 4, v18
	v_and_b32_e32 v3, 32, v0
	v_mul_i32_i24_e32 v2, 0x2e40, v2
	s_bfe_i32 s5, s24, 0x10014
	v_or3_b32 v2, v2, v3, v20
	v_or_b32_e32 v3, s4, v21
	s_lshr_b32 s5, s5, 24
	v_add_u32_e32 v4, s5, v3
	v_ashrrev_i32_e32 v6, 8, v4
	v_and_b32_e32 v4, 0xffffff00, v4
	v_sub_u32_e32 v4, v3, v4
	v_or_b32_e32 v3, 0x400, v3
	v_add_u32_e32 v10, s5, v3
	v_ashrrev_i32_e32 v12, 8, v10
	v_and_b32_e32 v10, 0xffffff00, v10
	v_lshlrev_b32_e32 v5, 4, v6
	v_sub_u32_e32 v3, v3, v10
	v_lshlrev_b32_e32 v10, 4, v12
	s_add_i32 s24, s4, 0
	s_mul_i32 s4, s7, 0x2e40
	s_mov_b32 s5, s45
	s_add_i32 s21, s21, 0x14000
	v_bitop3_b32 v8, v4, v5, s94 bitop3:0x78
	v_mul_hi_i32_i24_e32 v5, 0x5c80, v6
	v_mul_i32_i24_e32 v4, 0x5c80, v6
	v_bitop3_b32 v3, v3, v10, s94 bitop3:0x78
	v_mul_hi_i32_i24_e32 v11, 0x5c80, v12
	v_mul_i32_i24_e32 v10, 0x5c80, v12
	s_lshl_b64 s[4:5], s[4:5], 1
	v_lshl_add_u64 v[6:7], s[8:9], 0, v[4:5]
	v_ashrrev_i32_e32 v8, 1, v8
	v_lshl_add_u64 v[12:13], s[8:9], 0, v[10:11]
	v_ashrrev_i32_e32 v14, 1, v3
	s_add_u32 s8, s10, s4
	v_ashrrev_i32_e32 v3, 31, v2
	v_ashrrev_i32_e32 v9, 31, v8
	s_addc_u32 s9, s11, s5
	v_lshlrev_b64 v[2:3], 1, v[2:3]
	v_lshlrev_b64 v[8:9], 1, v[8:9]
	v_ashrrev_i32_e32 v15, 31, v14
	v_lshl_add_u64 v[16:17], s[8:9], 0, v[2:3]
	s_mov_b32 m0, s24
	v_lshl_add_u64 v[6:7], v[6:7], 0, v[8:9]
	v_lshlrev_b64 v[14:15], 1, v[14:15]
	global_load_lds_dwordx4 v[16:17], off
	v_lshl_add_u64 v[16:17], v[16:17], 0, s[40:41]
	s_add_i32 m0, s24, 0x400
	v_lshl_add_u64 v[12:13], v[12:13], 0, v[14:15]
	global_load_lds_dwordx4 v[16:17], off
	s_add_i32 m0, s24, 0x8000
	v_lshl_add_u64 v[6:7], v[6:7], 0, s[4:5]
	global_load_lds_dwordx4 v[6:7], off
	v_lshl_add_u64 v[6:7], v[12:13], 0, s[4:5]
	s_add_i32 m0, s24, 0x8400
	v_lshlrev_b32_e32 v12, 1, v0
	global_load_lds_dwordx4 v[6:7], off
	v_lshlrev_b32_e32 v0, 4, v0
	v_and_b32_e32 v13, 0x70, v0
	s_movk_i32 s8, 0x60
	v_bitop3_b32 v149, v130, v13, s8 bitop3:0x36
	s_movk_i32 s8, 0x80
	v_bitop3_b32 v148, v130, v13, s8 bitop3:0x36
	s_movk_i32 s8, 0xa0
	v_bitop3_b32 v147, v130, v13, s8 bitop3:0x36
	s_movk_i32 s8, 0xc0
	v_and_b32_e32 v6, 0x100, v19
	v_and_b32_e32 v7, 0xc0, v21
	v_bitop3_b32 v146, v130, v13, s8 bitop3:0x36
	s_movk_i32 s8, 0xe0
	s_cmp_lg_u32 0, -1
	v_and_b32_e32 v12, 32, v12
	v_bitop3_b32 v152, v130, v0, s94 bitop3:0x78
	v_bitop3_b32 v145, v130, v13, s8 bitop3:0x36
	v_or3_b32 v0, v7, v6, v20
	s_cselect_b32 s8, 0, 0
	v_add3_u32 v142, v12, s8, v0
	s_mul_i32 s8, s6, 0x2e4000
	s_add_i32 s8, s8, 0xb9b8000
	s_mov_b32 s9, s45
	s_lshl_b64 s[8:9], s[8:9], 1
	v_readlane_b32 s10, v249, 0
	v_readlane_b32 s11, v249, 1
	s_add_u32 s10, s10, s8
	s_addc_u32 s11, s11, s9
	s_add_u32 s10, s10, s44
	s_addc_u32 s11, s11, 0
	v_lshl_add_u64 v[132:133], s[10:11], 0, v[2:3]
	v_readlane_b32 s10, v250, 61
	v_lshl_add_u64 v[2:3], v[4:5], 0, s[44:45]
	s_add_u32 s8, s10, s8
	v_readlane_b32 s10, v250, 62
	v_lshl_add_u64 v[2:3], v[2:3], 0, v[8:9]
	s_addc_u32 s9, s10, s9
	v_lshl_add_u64 v[134:135], s[8:9], 0, v[2:3]
	v_lshl_add_u64 v[2:3], v[10:11], 0, s[44:45]
	v_lshl_add_u64 v[2:3], v[2:3], 0, v[14:15]
	v_mov_b32_e32 v14, v1
	v_mov_b32_e32 v15, v1
	s_waitcnt vmcnt(0)
	v_cmp_gt_u32_e64 s[4:5], 32, v18
	v_bitop3_b32 v151, v130, v13, 32 bitop3:0x36
	v_bitop3_b32 v150, v130, v13, 64 bitop3:0x36
	v_lshl_add_u64 v[136:137], s[8:9], 0, v[2:3]
	v_mov_b32_e32 v0, v1
	v_mov_b32_e32 v2, v1
	v_mov_b32_e32 v3, v1
	v_mov_b32_e32 v4, v1
	v_mov_b32_e32 v5, v1
	v_mov_b32_e32 v6, v1
	v_mov_b32_e32 v7, v1
	v_mov_b32_e32 v8, v1
	v_mov_b32_e32 v9, v1
	v_mov_b32_e32 v10, v1
	v_mov_b32_e32 v11, v1
	v_mov_b32_e32 v12, v1
	v_mov_b32_e32 v13, v1
	v_mov_b64_e32 v[64:65], v[14:15]
	v_mov_b64_e32 v[48:49], v[14:15]
	v_mov_b64_e32 v[32:33], v[14:15]
	v_mov_b64_e32 v[62:63], v[12:13]
	v_mov_b64_e32 v[60:61], v[10:11]
	v_mov_b64_e32 v[58:59], v[8:9]
	v_mov_b64_e32 v[56:57], v[6:7]
	v_mov_b64_e32 v[54:55], v[4:5]
	v_mov_b64_e32 v[52:53], v[2:3]
	v_mov_b64_e32 v[50:51], v[0:1]
	v_mov_b64_e32 v[46:47], v[12:13]
	v_mov_b64_e32 v[44:45], v[10:11]
	v_mov_b64_e32 v[42:43], v[8:9]
	v_mov_b64_e32 v[40:41], v[6:7]
	v_mov_b64_e32 v[38:39], v[4:5]
	v_mov_b64_e32 v[36:37], v[2:3]
	v_mov_b64_e32 v[34:35], v[0:1]
	v_mov_b64_e32 v[30:31], v[12:13]
	v_mov_b64_e32 v[28:29], v[10:11]
	v_mov_b64_e32 v[26:27], v[8:9]
	v_mov_b64_e32 v[24:25], v[6:7]
	v_mov_b64_e32 v[22:23], v[4:5]
	v_mov_b64_e32 v[20:21], v[2:3]
	v_mov_b64_e32 v[18:19], v[0:1]
	v_mov_b64_e32 v[16:17], v[14:15]
	v_lshl_add_u32 v144, v141, 8, 0
	v_lshl_add_u32 v131, v141, 2, s21
	s_mov_b32 s25, 0
	v_mov_b32_e32 v153, 0
	v_mov_b32_e32 v143, 0xf149f2ca
	s_mov_b64 s[8:9], 0
	s_movk_i32 s26, 0x4000
	v_mov_b64_e32 v[14:15], v[12:13]
	v_mov_b64_e32 v[12:13], v[10:11]
	v_mov_b64_e32 v[10:11], v[8:9]
	v_mov_b64_e32 v[8:9], v[6:7]
	v_mov_b64_e32 v[6:7], v[4:5]
	v_mov_b64_e32 v[4:5], v[2:3]
	v_mov_b64_e32 v[2:3], v[0:1]
	s_waitcnt vmcnt(0) lgkmcnt(0)
	s_barrier
	.p2align	6

; template <int DQK, bool NA>
; __device__ __forceinline__ void attn_unit(const UnitP& P, char* lds) {
;     ...
;     bf16x8 qr[NQ];
;     { const bf16_t* Qw = P.Q + (size_t)(wid * 32 + r32) * P.ldq + hi * 8;
; #pragma unroll
;       for (int d0 = 0; d0 < NQ; ++d0) qr[d0] = *reinterpret_cast<const bf16x8*>(Qw + d0 * 16); }
;     if constexpr (DQK == 192) {
;         if (P.rope_q) {
;             const int s = P.qpos0 + wid * 32 + r32; const float prow = (float)(s >> 6), pcol = (float)(s & 63);
; #pragma unroll
;             for (int e = 0; e < 8; ++e) {
;                 const float fr_ = __builtin_amdgcn_exp2f(-(float)(hi * 8 + e) * (13.287712379549449f / 16.f));
;                 const float ar = prow * fr_, ac = pcol * fr_;
;                 const float cr = __cosf(ar), sr = __sinf(ar), cc = __cosf(ac), sc = __sinf(ac);
;                 const float x1 = bf2f((unsigned short)qr[8][e]), x2 = bf2f((unsigned short)qr[9][e]), y1 = bf2f((unsigned short)qr[10][e]), y2 = bf2f((unsigned short)qr[11][e]);
;                 const unsigned w0 = cvtpk(x1 * cr - x2 * sr, x2 * cr + x1 * sr), w1 = cvtpk(y1 * cc - y2 * sc, y2 * cc + y1 * sc);
;                 qr[8][e] = (short)(w0 & 0xffffu); qr[9][e] = (short)(w0 >> 16); qr[10][e] = (short)(w1 & 0xffffu); qr[11][e] = (short)(w1 >> 16);
;             }
;         }
;     }
;     const int vb0 = (int)(uintptr_t)V_lds + v_rd_base(lane);
;     ...
;     LAS char* ldsl = (LAS char*)lds;
;     constexpr int NKI = DQK / 64;
;     int voffe[2]; const bf16_t* kbase[NKI]; int kld[NKI];
; #pragma unroll
;     for (int j = 0; j < 2; ++j) { const int X = (wid * 2 + j) * 1024 + lane * 16, st = X >> 9, kk = ((st >> 2) << 3) | ((X >> 6) & 7), c = ((st & 3) << 5) | ((X >> 1) & 31);
;         const int k = (kk & ~0xC) | ((kk & 4) << 1) | ((kk & 8) >> 1); voffe[j] = k * P.ldv + c; }
; #pragma unroll
;     for (int j = 0; j < NKI; ++j) { const int X = (wid * NKI + j) * 1024 + lane * 16, row = X / KROWB, cb = X - row * KROWB, colB = cb ^ ((row & 7) << 4);
;         if (DQK == 192 && colB >= 256) { kbase[j] = P.K2 + (size_t)row * P.ldk2 + ((colB - 256) >> 1); kld[j] = P.ldk2; }
;         else { kbase[j] = P.K1 + (size_t)row * P.ldk1 + (colB >> 1); kld[j] = P.ldk1; } }
;     ...
;     const int qgrow = P.qgrow0 + (wid >> 1), qc = (wid & 1) * 32 + r32;
;     const int r0w = min(max(qgrow - 4, 0), 24), c0 = min(max(qc - 8, 0), 48);
.LBB0_610:
	s_andn2_b64 vcc, exec, s[4:5]
	s_cbranch_vccnz .LBB0_565
	s_mul_i32 s4, s16, 0x5c80
	s_mul_hi_u32 s5, s15, 0x5c80
	s_lshl_b32 s44, s18, 8
	s_add_i32 s5, s5, s4
	s_mul_i32 s4, s15, 0x5c80
	s_add_u32 s4, s84, s4
	s_addc_u32 s5, s85, s5
	s_lshl_b32 s10, s17, 7
	s_lshl_b32 s11, s17, 8
	s_add_u32 s4, s4, s11
	s_addc_u32 s5, s5, 0
	v_readlane_b32 s8, v252, 26
	s_add_u32 s8, s8, s11
	v_readlane_b32 s9, v252, 27
	s_addc_u32 s9, s9, 0
	v_readlane_b32 s17, v252, 28
	s_add_u32 s19, s17, s11
	v_readlane_b32 s11, v252, 29
	v_mov_b32_e32 v0, v196
	s_addc_u32 s20, s11, 0
	v_mov_b64_e32 v[2:3], s[4:5]
	v_readfirstlane_b32 s11, v0
	s_ashr_i32 s18, s11, 6
	s_and_b32 s11, s11, 0x3fffffc0
	s_lshl_b32 s11, s11, 2
	v_and_b32_e32 v141, 31, v0
	s_add_i32 s17, s11, 0
	s_lshl_b32 s11, s18, 5
	v_or_b32_e32 v4, s11, v141
	v_bfe_u32 v140, v0, 5, 1
	v_mad_i64_i32 v[2:3], s[4:5], v4, s71, v[2:3]
	v_lshlrev_b32_e32 v130, 4, v140
	v_mov_b32_e32 v131, v1
	s_lshl_b32 s4, s18, 11
	v_lshl_add_u64 v[2:3], v[2:3], 0, v[130:131]
	s_ashr_i32 s5, s4, 8
	v_lshrrev_b32_e32 v4, 1, v0
	global_load_dwordx4 v[126:129], v[2:3], off
	global_load_dwordx4 v[122:125], v[2:3], off offset:32
	global_load_dwordx4 v[118:121], v[2:3], off offset:64
	global_load_dwordx4 v[114:117], v[2:3], off offset:96
	global_load_dwordx4 v[110:113], v[2:3], off offset:128
	global_load_dwordx4 v[106:109], v[2:3], off offset:160
	global_load_dwordx4 v[102:105], v[2:3], off offset:192
	global_load_dwordx4 v[98:101], v[2:3], off offset:224
	v_bfe_u32 v2, v0, 2, 2
	s_and_b32 s21, s5, 0xfffff0
	v_and_b32_e32 v4, 8, v4
	v_and_b32_e32 v18, 63, v0
	s_lshr_b32 s5, s5, 1
	v_or3_b32 v2, v4, v2, s21
	v_lshlrev_b32_e32 v19, 3, v18
	v_and_or_b32 v2, s5, 4, v2
	v_and_b32_e32 v20, 24, v19
	v_lshlrev_b32_e32 v21, 4, v18
	v_and_b32_e32 v3, 32, v0
	v_mul_i32_i24_e32 v2, 0x2e40, v2
	s_bfe_i32 s5, s18, 0x10014
	v_or3_b32 v2, v2, v3, v20
	v_or_b32_e32 v3, s4, v21
	s_lshr_b32 s5, s5, 24
	v_add_u32_e32 v4, s5, v3
	v_ashrrev_i32_e32 v6, 8, v4
	v_and_b32_e32 v4, 0xffffff00, v4
	v_sub_u32_e32 v4, v3, v4
	v_or_b32_e32 v3, 0x400, v3
	v_add_u32_e32 v10, s5, v3
	v_ashrrev_i32_e32 v12, 8, v10
	v_and_b32_e32 v10, 0xffffff00, v10
	v_lshlrev_b32_e32 v5, 4, v6
	v_sub_u32_e32 v3, v3, v10
	v_lshlrev_b32_e32 v10, 4, v12
	s_add_i32 s17, s17, 0x14000
	v_bitop3_b32 v8, v4, v5, s94 bitop3:0x78
	v_bitop3_b32 v3, v3, v10, s94 bitop3:0x78
	s_add_i32 s18, s4, 0
	s_mul_i32 s4, s7, 0x5c80
	v_ashrrev_i32_e32 v8, 1, v8
	v_ashrrev_i32_e32 v14, 1, v3
	s_mul_hi_u32 s5, s7, 0x5c80
	s_add_u32 s4, s19, s4
	v_ashrrev_i32_e32 v3, 31, v2
	v_mul_hi_i32_i24_e32 v5, 0x5c80, v6
	v_mul_i32_i24_e32 v4, 0x5c80, v6
	v_ashrrev_i32_e32 v9, 31, v8
	s_addc_u32 s5, s20, s5
	v_lshlrev_b64 v[2:3], 1, v[2:3]
	v_lshl_add_u64 v[6:7], s[8:9], 0, v[4:5]
	v_lshlrev_b64 v[8:9], 1, v[8:9]
	v_mul_hi_i32_i24_e32 v11, 0x5c80, v12
	v_mul_i32_i24_e32 v10, 0x5c80, v12
	v_ashrrev_i32_e32 v15, 31, v14
	v_lshl_add_u64 v[16:17], s[4:5], 0, v[2:3]
	s_mov_b32 m0, s18
	v_lshl_add_u64 v[6:7], v[6:7], 0, v[8:9]
	v_lshl_add_u64 v[12:13], s[8:9], 0, v[10:11]
	v_lshlrev_b64 v[14:15], 1, v[14:15]
	global_load_lds_dwordx4 v[16:17], off
	v_lshl_add_u64 v[16:17], v[16:17], 0, s[40:41]
	s_add_i32 m0, s18, 0x400
	v_lshl_add_u64 v[12:13], v[12:13], 0, v[14:15]
	global_load_lds_dwordx4 v[16:17], off
	s_add_i32 m0, s18, 0x8000
	v_mad_u64_u32 v[6:7], s[4:5], s7, v241, v[6:7]
	global_load_lds_dwordx4 v[6:7], off
	v_mad_u64_u32 v[6:7], s[4:5], s7, v241, v[12:13]
	s_add_i32 m0, s18, 0x8400
	v_lshlrev_b32_e32 v12, 1, v0
	global_load_lds_dwordx4 v[6:7], off
	v_lshlrev_b32_e32 v0, 4, v0
	v_and_b32_e32 v13, 0x70, v0
	s_movk_i32 s7, 0x60
	v_bitop3_b32 v149, v130, v13, s7 bitop3:0x36
	s_movk_i32 s7, 0x80
	v_bitop3_b32 v148, v130, v13, s7 bitop3:0x36
	s_movk_i32 s7, 0xa0
	v_bitop3_b32 v147, v130, v13, s7 bitop3:0x36
	s_movk_i32 s7, 0xc0
	v_and_b32_e32 v6, 0x100, v19
	v_and_b32_e32 v7, 0xc0, v21
	v_bitop3_b32 v146, v130, v13, s7 bitop3:0x36
	s_movk_i32 s7, 0xe0
	s_cmp_lg_u32 0, -1
	v_and_b32_e32 v12, 32, v12
	v_bitop3_b32 v152, v130, v0, s94 bitop3:0x78
	v_bitop3_b32 v145, v130, v13, s7 bitop3:0x36
	v_or3_b32 v0, v7, v6, v20
	s_cselect_b32 s7, 0, 0
	s_mul_i32 s6, s6, 0x2e4000
	v_add3_u32 v142, v12, s7, v0
	s_add_i32 s6, s6, 0xb9b8000
	s_mov_b32 s7, s45
	s_lshl_b64 s[6:7], s[6:7], 1
	v_readlane_b32 s8, v249, 0
	v_readlane_b32 s9, v249, 1
	s_add_u32 s8, s8, s6
	s_addc_u32 s9, s9, s7
	s_add_u32 s8, s8, s44
	s_addc_u32 s9, s9, 0
	v_lshl_add_u64 v[132:133], s[8:9], 0, v[2:3]
	v_readlane_b32 s8, v250, 63
	v_lshl_add_u64 v[2:3], v[4:5], 0, s[44:45]
	s_add_u32 s6, s8, s6
	v_readlane_b32 s8, v249, 2
	v_lshl_add_u64 v[2:3], v[2:3], 0, v[8:9]
	s_addc_u32 s7, s8, s7
	v_lshl_add_u64 v[134:135], s[6:7], 0, v[2:3]
	v_lshl_add_u64 v[2:3], v[10:11], 0, s[44:45]
	v_lshl_add_u64 v[2:3], v[2:3], 0, v[14:15]
	v_mov_b32_e32 v14, v1
	v_mov_b32_e32 v15, v1
	s_waitcnt vmcnt(0)
	v_cmp_gt_u32_e64 s[4:5], 32, v18
	v_bitop3_b32 v151, v130, v13, 32 bitop3:0x36
	v_bitop3_b32 v150, v130, v13, 64 bitop3:0x36
	v_lshl_add_u64 v[136:137], s[6:7], 0, v[2:3]
	v_mov_b32_e32 v0, v1
	v_mov_b32_e32 v2, v1
	v_mov_b32_e32 v3, v1
	v_mov_b32_e32 v4, v1
	v_mov_b32_e32 v5, v1
	v_mov_b32_e32 v6, v1
	v_mov_b32_e32 v7, v1
	v_mov_b32_e32 v8, v1
	v_mov_b32_e32 v9, v1
	v_mov_b32_e32 v10, v1
	v_mov_b32_e32 v11, v1
	v_mov_b32_e32 v12, v1
	v_mov_b32_e32 v13, v1
	v_mov_b64_e32 v[64:65], v[14:15]
	v_mov_b64_e32 v[48:49], v[14:15]
	v_mov_b64_e32 v[32:33], v[14:15]
	v_mov_b64_e32 v[62:63], v[12:13]
	v_mov_b64_e32 v[60:61], v[10:11]
	v_mov_b64_e32 v[58:59], v[8:9]
	v_mov_b64_e32 v[56:57], v[6:7]
	v_mov_b64_e32 v[54:55], v[4:5]
	v_mov_b64_e32 v[52:53], v[2:3]
	v_mov_b64_e32 v[50:51], v[0:1]
	v_mov_b64_e32 v[46:47], v[12:13]
	v_mov_b64_e32 v[44:45], v[10:11]
	v_mov_b64_e32 v[42:43], v[8:9]
	v_mov_b64_e32 v[40:41], v[6:7]
	v_mov_b64_e32 v[38:39], v[4:5]
	v_mov_b64_e32 v[36:37], v[2:3]
	v_mov_b64_e32 v[34:35], v[0:1]
	v_mov_b64_e32 v[30:31], v[12:13]
	v_mov_b64_e32 v[28:29], v[10:11]
	v_mov_b64_e32 v[26:27], v[8:9]
	v_mov_b64_e32 v[24:25], v[6:7]
	v_mov_b64_e32 v[22:23], v[4:5]
	v_mov_b64_e32 v[20:21], v[2:3]
	v_mov_b64_e32 v[18:19], v[0:1]
	v_mov_b64_e32 v[16:17], v[14:15]
	v_lshl_add_u32 v144, v141, 8, 0
	v_lshl_add_u32 v131, v141, 2, s17
	s_mov_b32 s19, 0
	v_mov_b32_e32 v153, 0
	v_mov_b32_e32 v143, 0xf149f2ca
	s_mov_b64 s[6:7], 0
	s_movk_i32 s20, 0x4000
	v_mov_b64_e32 v[14:15], v[12:13]
	v_mov_b64_e32 v[12:13], v[10:11]
	v_mov_b64_e32 v[10:11], v[8:9]
	v_mov_b64_e32 v[8:9], v[6:7]
	v_mov_b64_e32 v[6:7], v[4:5]
	v_mov_b64_e32 v[4:5], v[2:3]
	v_mov_b64_e32 v[2:3], v[0:1]
	s_waitcnt vmcnt(0) lgkmcnt(0)
	s_barrier
	.p2align	6
